# phase-0 weight conversion rewritten by hand: 4-slot software-pipelined f32->bf16 transpose tiles with 3 tiles of loads in flight, done by workgroups 8..255 (0..7 only build S5 tables)
# speedup vs baseline: 1.0149x; 1.0149x over previous
; #define LAS __attribute__((address_space(3)))
; __global__ void __launch_bounds__(512, 2) fwd_megakernel(Params p) {
;     extern __shared__ __attribute__((aligned(16))) unsigned char smem[];
;     cg::grid_group grid = cg::this_grid();
;     LAS unsigned char* lds = (LAS unsigned char*)smem;
;     unsigned char* ws = p.ws;
;     u16* HN = (u16*)(ws + OFF_HN); u16* PROJ = (u16*)(ws + OFF_PROJ); float* GATES = (float*)(ws + OFF_GATES);
;     float* H = p.out;
;     unsigned* bar = (unsigned*)(ws + OFF_BAR);
;     volatile LAS unsigned* st = (volatile LAS unsigned*)(lds + LDS_MAIN);
;     if (blockIdx.x == 0) for (int i = threadIdx.x; i < XCD_BAR_WORDS; i += 512) bar[i] = 0u;
;     if (threadIdx.x == 0) { st[0] = 0u; st[1] = 0u; }
;     grid.sync();
;     const XcdBarrier xb = xcd_barrier_post(bar, st);
;     { int base = 0;
;       for (int job = 0; job < 33; ++job) { const float* src; const float* gk; int K, N, Npad, mode; u16* dst; conv_job(p, job, src, K, N, dst, Npad, mode, gk);
;         const int G = gridDim.x; int first = ((int)blockIdx.x - base) % G; if (first < 0) first += G;
;         convT(src, K, N, dst, Npad, mode, gk, (float*)smem, first); base += (K / 64) * (Npad / 64); } }
_Z14fwd_megakernel6Params:
	v_writelane_b32 v255, s0, 0
	v_writelane_b32 v255, s1, 1
	s_load_dwordx4 s[20:23], s[0:1], 0x120
	s_mov_b32 s33, s2
	s_load_dword s2, s[0:1], 0x130
	s_add_u32 s4, s0, 0x128
	s_addc_u32 s5, s1, 0
	s_waitcnt lgkmcnt(0)
	s_add_u32 s6, s20, 0x1da40000
	s_addc_u32 s7, s21, 0
	v_writelane_b32 v251, s2, 0
	s_mov_b32 s8, 0
	s_cmp_lg_u32 s33, 0
	v_and_b32_e32 v154, 0x3ff, v0
	s_cbranch_scc1 .LBB0_8
	v_sub_u32_e32 v1, 0xd7f, v154
	v_lshrrev_b32_e32 v2, 9, v1
	v_add_u32_e32 v1, 2, v2
	v_add_u32_e32 v155, 0x200, v154
	v_and_b32_e32 v3, 14, v1
	v_mov_b32_e32 v1, v2
	s_mov_b64 s[10:11], 0
	s_mov_b32 s9, 1
	v_mov_b32_e32 v5, 0
	s_mov_b32 s12, s8
	v_mov_b64_e32 v[6:7], v[154:155]
	s_branch .LBB0_3

; DEVI int otid() { int t = threadIdx.x; asm volatile("" : "+v"(t)); return t; }
; DEVI void convT(const float* src, int K, int N, u16* dst, int Npad, int mode, const float* gk, float* tile, int first) {
;     const int tid = otid(), ntk = K / 64, ntn = Npad / 64;
;     for (int ti = first; ti < ntk * ntn; ti += gridDim.x) {
;         const int k0 = (ti % ntk) * 64, n0 = (ti / ntk) * 64;
;         for (int i = tid; i < 1024; i += 512) { const int kk = i >> 4, n4 = (i & 15) * 4, n = n0 + n4;
;             f32x4 v = (f32x4){0.f, 0.f, 0.f, 0.f}; if (n < N) { v = *(const f32x4*)(src + (size_t)(k0 + kk) * N + n); if (gk) v = v * gk[k0 + kk]; }
;             float* tp = tile + kk * 65 + n4; tp[0] = v[0]; tp[1] = v[1]; tp[2] = v[2]; tp[3] = v[3]; }
; __global__ void __launch_bounds__(512, 2) fwd_megakernel(Params p) {
;     ...
;       for (int job = 0; job < 33; ++job) { const float* src; const float* gk; int K, N, Npad, mode; u16* dst; conv_job(p, job, src, K, N, dst, Npad, mode, gk);
;         const int G = gridDim.x; int first = ((int)blockIdx.x - base) % G; if (first < 0) first += G;
;         convT(src, K, N, dst, Npad, mode, gk, (float*)smem, first); base += (K / 64) * (Npad / 64); } }
.LBB0_23:
	s_or_b64 exec, exec, s[0:1]
	s_add_u32 s0, s20, 0x1d80000
	s_addc_u32 s1, s21, 0
	v_writelane_b32 v251, s0, 56
	s_mov_b32 s11, 0
	v_mov_b32_e32 v5, 0
	v_writelane_b32 v251, s1, 57
	s_add_u32 s0, s20, 0x1b80000
	s_addc_u32 s1, s21, 0
	v_writelane_b32 v251, s0, 58
	s_nop 1
	v_writelane_b32 v251, s1, 59
	s_add_u32 s0, s20, 0x1980000
	s_addc_u32 s1, s21, 0
	v_writelane_b32 v251, s0, 60
	s_nop 1
	v_writelane_b32 v251, s1, 61
	s_nop 0
	v_readlane_b32 s36, v251, 8
	v_readlane_b32 s40, v251, 12
	v_readlane_b32 s41, v251, 13
	s_add_u32 s0, s40, 0x2000
	s_addc_u32 s1, s41, 0
	s_add_u32 s2, s20, 0x1780000
	s_addc_u32 s3, s21, 0
	v_readlane_b32 s37, v251, 9
	v_readlane_b32 s38, v251, 10
	v_readlane_b32 s39, v251, 11
	v_readlane_b32 s42, v251, 14
	v_readlane_b32 s43, v251, 15
	v_readlane_b32 s44, v251, 16
	v_readlane_b32 s45, v251, 17
	v_readlane_b32 s46, v251, 18
	v_readlane_b32 s47, v251, 19
	v_readlane_b32 s48, v251, 20
	v_readlane_b32 s49, v251, 21
	v_readlane_b32 s50, v251, 22
	v_readlane_b32 s51, v251, 23
	v_writelane_b32 v251, s2, 62
	s_movk_i32 s46, 0x104
	s_mov_b32 s48, 0
	v_writelane_b32 v251, s3, 63
	s_add_u32 s2, s20, 0x1100000
	s_addc_u32 s3, s21, 0
	s_add_u32 s8, s40, 0x1000
	v_writelane_b32 v252, s2, 0
	s_addc_u32 s9, s41, 0
	s_mov_b32 s49, 0
	v_writelane_b32 v252, s3, 1
	s_add_u32 s2, s20, 0x6b80000
	v_writelane_b32 v252, s2, 2
	s_addc_u32 s2, s21, 0
	v_writelane_b32 v252, s2, 3
	s_add_u32 s2, s20, 0x3f80000
	v_writelane_b32 v252, s2, 4
	s_addc_u32 s2, s21, 0
	v_writelane_b32 v252, s2, 5
	s_add_u32 s2, s20, 0x3780000
	v_writelane_b32 v252, s2, 6
	s_addc_u32 s2, s21, 0
	s_add_u32 s80, s20, 0x2780000
	v_writelane_b32 v252, s2, 7
	s_addc_u32 s2, s21, 0
	v_writelane_b32 v252, s2, 8
	s_add_u32 s2, s20, 0x1f80000
	v_writelane_b32 v252, s2, 10
	s_addc_u32 s2, s21, 0
	v_writelane_b32 v252, s2, 11
	s_add_u32 s2, s20, 0xd00000
	v_writelane_b32 v252, s2, 12
	s_addc_u32 s2, s21, 0
	s_abs_i32 s19, s22
	v_writelane_b32 v252, s2, 13
	v_cvt_f32_u32_e32 v0, s19
	v_writelane_b32 v252, s60, 14
	s_sub_i32 s4, 0, s19
	v_rcp_iflag_f32_e32 v0, v0
	v_writelane_b32 v252, s61, 15
	v_writelane_b32 v252, s62, 16
	v_writelane_b32 v252, s63, 17
	v_writelane_b32 v252, s64, 18
	v_writelane_b32 v252, s65, 19
	v_writelane_b32 v252, s66, 20
	v_mul_f32_e32 v0, 0x4f7ffffe, v0
	v_writelane_b32 v252, s67, 21
	v_cvt_u32_f32_e32 v0, v0
	v_writelane_b32 v252, s68, 22
	v_writelane_b32 v252, s69, 23
	v_writelane_b32 v252, s70, 24
	v_writelane_b32 v252, s71, 25
	v_readfirstlane_b32 s5, v0
	v_writelane_b32 v252, s72, 26
	s_mul_i32 s4, s4, s5
	v_writelane_b32 v252, s73, 27
	s_mul_hi_u32 s4, s5, s4
	v_writelane_b32 v252, s74, 28
	s_add_i32 s47, s5, s4
	v_writelane_b32 v252, s75, 29
	s_cmp_lt_u32 s33, 8
	s_cbranch_scc1 .Lcv_end
	v_readlane_b32 s34, v255, 0
	v_readlane_b32 s35, v255, 1
	s_sub_u32 s39, s33, 8
	s_cmp_lt_u32 s39, 208
	s_cselect_b32 s37, 1, 0
	s_add_u32 s37, s37, 66
	v_lshrrev_b32_e32 v1, 4, v154
	v_and_b32_e32 v3, 15, v154
	v_lshlrev_b32_e32 v2, 4, v3
	v_lshlrev_b32_e32 v3, 2, v3
	v_lshlrev_b32_e32 v4, 2, v1
	v_mul_u32_u24_e32 v6, 65, v1
	v_add_lshl_u32 v6, v6, v3, 2
	v_add_u32_e32 v7, 8320, v6
	v_add_u32_e32 v8, 16640, v6
	v_add_u32_e32 v9, 16640, v7
	v_and_b32_e32 v17, 7, v154
	v_lshrrev_b32_e32 v16, 3, v154
	v_mul_u32_u24_e32 v10, 520, v17
	v_add_lshl_u32 v10, v10, v16, 2
	v_add_u32_e32 v11, 1024, v10
	v_add_u32_e32 v12, 16640, v10
	v_add_u32_e32 v13, 16640, v11
	v_mul_u32_u24_e32 v14, 65, v16
	v_lshlrev_b32_e32 v19, 3, v17
	v_add_lshl_u32 v14, v14, v19, 2
	v_add_u32_e32 v15, 16640, v14
	v_lshlrev_b32_e32 v17, 4, v17
	v_lshl_add_u32 v18, v16, 11, v17
	s_mov_b32 s38, 0
	s_add_u32 s38, s38, s39
	s_mov_b32 s79, 0
	s_branch .Lcv_desc
.Lcv_ret0:
	v_cmp_gt_i32_e32 vcc, s63, v3
	v_add_u32_e32 v70, s64, v2
	s_nop 1
	v_cndmask_b32_e32 v70, 0, v70, vcc
	v_mad_u32_u24 v70, v1, s62, v70
	global_load_dwordx4 v[20:23], v70, s[60:61]
	s_lshl_b32 s2, s62, 5
	s_add_u32 s60, s60, s2
	s_addc_u32 s61, s61, 0
	global_load_dwordx4 v[24:27], v70, s[60:61]
	global_load_dword v28, v4, s[66:67]
	global_load_dword v29, v4, s[66:67] offset:128
	s_mov_b64 s[40:41], s[70:71]
	s_mov_b32 s42, s63
	s_mov_b32 s43, s68
	s_mul_i32 s38, 1, 248
	s_add_u32 s38, s38, s39
	s_mov_b32 s79, 1
	s_branch .Lcv_desc
.Lcv_ret1:
	v_cmp_gt_i32_e32 vcc, s63, v3
	v_add_u32_e32 v70, s64, v2
	s_nop 1
	v_cndmask_b32_e32 v70, 0, v70, vcc
	v_mad_u32_u24 v70, v1, s62, v70
	global_load_dwordx4 v[32:35], v70, s[60:61]
	s_lshl_b32 s2, s62, 5
	s_add_u32 s60, s60, s2
	s_addc_u32 s61, s61, 0
	global_load_dwordx4 v[36:39], v70, s[60:61]
	global_load_dword v40, v4, s[66:67]
	global_load_dword v41, v4, s[66:67] offset:128
	s_mov_b64 s[44:45], s[70:71]
	s_mov_b32 s50, s63
	s_mov_b32 s51, s68
	s_mul_i32 s38, 2, 248
	s_add_u32 s38, s38, s39
	s_mov_b32 s79, 2
	s_branch .Lcv_desc
.Lcv_ret2:
	v_cmp_gt_i32_e32 vcc, s63, v3
	v_add_u32_e32 v70, s64, v2
	s_nop 1
	v_cndmask_b32_e32 v70, 0, v70, vcc
	v_mad_u32_u24 v70, v1, s62, v70
	global_load_dwordx4 v[44:47], v70, s[60:61]
	s_lshl_b32 s2, s62, 5
	s_add_u32 s60, s60, s2
	s_addc_u32 s61, s61, 0
	global_load_dwordx4 v[48:51], v70, s[60:61]
	global_load_dword v52, v4, s[66:67]
	global_load_dword v53, v4, s[66:67] offset:128
	s_mov_b64 s[52:53], s[70:71]
	s_mov_b32 s54, s63
	s_mov_b32 s55, s68
	s_mov_b32 s36, 0
.Lcv_loop:
	s_add_u32 s38, s36, 3
	s_sub_u32 s2, s37, 1
	s_min_u32 s38, s38, s2
	s_mul_i32 s38, s38, 248
	s_add_u32 s38, s38, s39
	s_mov_b32 s79, 3
	s_branch .Lcv_desc
; DEVI unsigned cvt_pk(float lo, float hi) { f32v2_t f = {lo, hi}; bf16v2_t v = __builtin_convertvector(f, bf16v2_t); return __builtin_bit_cast(unsigned, v); }
; DEVI void convT(const float* src, int K, int N, u16* dst, int Npad, int mode, const float* gk, float* tile, int first) {
;     ...
;         for (int i = tid; i < 1024; i += 512) { const int kk = i >> 4, n4 = (i & 15) * 4, n = n0 + n4;
;             f32x4 v = (f32x4){0.f, 0.f, 0.f, 0.f}; if (n < N) { v = *(const f32x4*)(src + (size_t)(k0 + kk) * N + n); if (gk) v = v * gk[k0 + kk]; }
;             float* tp = tile + kk * 65 + n4; tp[0] = v[0]; tp[1] = v[1]; tp[2] = v[2]; tp[3] = v[3]; }
;         __syncthreads();
;         if (mode == 3) { const int kk = tid >> 3, n8 = (tid & 7) * 8; const float* tp = tile + kk * 65 + n8;
;           u32x4 w; w.x = cvt_pk(tp[0], tp[1]); w.y = cvt_pk(tp[2], tp[3]); w.z = cvt_pk(tp[4], tp[5]); w.w = cvt_pk(tp[6], tp[7]);
;           *(u32x4*)(dst + (size_t)(k0 + kk) * N + n0 + n8) = w; }
;         else { const int nn = tid >> 3, k8 = (tid & 7) * 8; const int n = n0 + nn;
;           int row = n; if (mode == 1) row = 256 * (n >> 7) + (n & 127); else if (mode == 2) row = 256 * (n >> 7) + 128 + (n & 127);
;           u32x4 w; w.x = cvt_pk(tile[(k8 + 0) * 65 + nn], tile[(k8 + 1) * 65 + nn]); w.y = cvt_pk(tile[(k8 + 2) * 65 + nn], tile[(k8 + 3) * 65 + nn]);
;           w.z = cvt_pk(tile[(k8 + 4) * 65 + nn], tile[(k8 + 5) * 65 + nn]); w.w = cvt_pk(tile[(k8 + 6) * 65 + nn], tile[(k8 + 7) * 65 + nn]);
;           *(u32x4*)(dst + (size_t)row * K + k0 + k8) = w; }
;         __syncthreads();
.Lcv_ret3:
	v_cmp_gt_i32_e32 vcc, s63, v3
	v_add_u32_e32 v70, s64, v2
	s_nop 1
	v_cndmask_b32_e32 v70, 0, v70, vcc
	v_mad_u32_u24 v70, v1, s62, v70
	global_load_dwordx4 v[56:59], v70, s[60:61]
	s_lshl_b32 s2, s62, 5
	s_add_u32 s60, s60, s2
	s_addc_u32 s61, s61, 0
	global_load_dwordx4 v[60:63], v70, s[60:61]
	global_load_dword v64, v4, s[66:67]
	global_load_dword v65, v4, s[66:67] offset:128
	s_mov_b64 s[56:57], s[70:71]
	s_mov_b32 s58, s63
	s_mov_b32 s59, s68
	s_waitcnt vmcnt(12)
	s_bitcmp1_b32 s43, 2
	s_cbranch_scc0 .Lcv_nogk0
	v_mul_f32_e32 v20, v20, v28
	v_mul_f32_e32 v21, v21, v28
	v_mul_f32_e32 v22, v22, v28
	v_mul_f32_e32 v23, v23, v28
	v_mul_f32_e32 v24, v24, v29
	v_mul_f32_e32 v25, v25, v29
	v_mul_f32_e32 v26, v26, v29
	v_mul_f32_e32 v27, v27, v29
.Lcv_nogk0:
	s_cmp_ge_i32 s42, 64
	s_cbranch_scc1 .Lcv_full0
	v_cmp_gt_i32_e32 vcc, s42, v3
	s_nop 1
	v_cndmask_b32_e32 v20, 0, v20, vcc
	v_cndmask_b32_e32 v21, 0, v21, vcc
	v_cndmask_b32_e32 v22, 0, v22, vcc
	v_cndmask_b32_e32 v23, 0, v23, vcc
	v_cndmask_b32_e32 v24, 0, v24, vcc
	v_cndmask_b32_e32 v25, 0, v25, vcc
	v_cndmask_b32_e32 v26, 0, v26, vcc
	v_cndmask_b32_e32 v27, 0, v27, vcc
.Lcv_full0:
	ds_write2_b32 v6, v20, v21 offset1:1
	ds_write2_b32 v6, v22, v23 offset0:2 offset1:3
	ds_write2_b32 v7, v24, v25 offset1:1
	ds_write2_b32 v7, v26, v27 offset0:2 offset1:3
	s_waitcnt lgkmcnt(0)
	s_barrier
	s_and_b32 s2, s43, 3
	s_cmp_eq_u32 s2, 3
	s_cbranch_scc1 .Lcv_m30
	ds_read2_b32 v[72:73], v10 offset1:65
	ds_read2_b32 v[74:75], v10 offset0:130 offset1:195
	ds_read2_b32 v[76:77], v11 offset0:4 offset1:69
	ds_read2_b32 v[78:79], v11 offset0:134 offset1:199
	s_bitcmp1_b32 s43, 3
	s_movk_i32 s2, 0x800
	s_cbranch_scc0 .Lcv_k0
	s_movk_i32 s2, 0x1600
.Lcv_k0:
	v_mad_u32_u24 v71, v16, s2, v17
	s_waitcnt lgkmcnt(0)
	v_cvt_pk_bf16_f32 v72, v72, v73
	v_cvt_pk_bf16_f32 v73, v74, v75
	v_cvt_pk_bf16_f32 v74, v76, v77
	v_cvt_pk_bf16_f32 v75, v78, v79
	global_store_dwordx4 v71, v[72:75], s[40:41]
	s_branch .Lcv_st0
.Lcv_m30:
	ds_read2_b32 v[72:73], v14 offset1:1
	ds_read2_b32 v[74:75], v14 offset0:2 offset1:3
	ds_read2_b32 v[76:77], v14 offset0:4 offset1:5
	ds_read2_b32 v[78:79], v14 offset0:6 offset1:7
	s_waitcnt lgkmcnt(0)
	v_cvt_pk_bf16_f32 v72, v72, v73
	v_cvt_pk_bf16_f32 v73, v74, v75
	v_cvt_pk_bf16_f32 v74, v76, v77
	v_cvt_pk_bf16_f32 v75, v78, v79
	global_store_dwordx4 v18, v[72:75], s[40:41]
.Lcv_st0:
	s_add_u32 s36, s36, 1
	s_cmp_ge_u32 s36, s37
	s_cbranch_scc1 .Lcv_done
	s_add_u32 s38, s36, 3
	s_sub_u32 s2, s37, 1
	s_min_u32 s38, s38, s2
	s_mul_i32 s38, s38, 248
	s_add_u32 s38, s38, s39
	s_mov_b32 s79, 4
	s_branch .Lcv_desc
.Lcv_ret4:
	v_cmp_gt_i32_e32 vcc, s63, v3
	v_add_u32_e32 v70, s64, v2
	s_nop 1
	v_cndmask_b32_e32 v70, 0, v70, vcc
	v_mad_u32_u24 v70, v1, s62, v70
	global_load_dwordx4 v[20:23], v70, s[60:61]
	s_lshl_b32 s2, s62, 5
	s_add_u32 s60, s60, s2
	s_addc_u32 s61, s61, 0
	global_load_dwordx4 v[24:27], v70, s[60:61]
	global_load_dword v28, v4, s[66:67]
	global_load_dword v29, v4, s[66:67] offset:128
	s_mov_b64 s[40:41], s[70:71]
	s_mov_b32 s42, s63
	s_mov_b32 s43, s68
	s_waitcnt vmcnt(12)
	s_bitcmp1_b32 s51, 2
	s_cbranch_scc0 .Lcv_nogk1
	v_mul_f32_e32 v32, v32, v40
	v_mul_f32_e32 v33, v33, v40
	v_mul_f32_e32 v34, v34, v40
	v_mul_f32_e32 v35, v35, v40
	v_mul_f32_e32 v36, v36, v41
	v_mul_f32_e32 v37, v37, v41
	v_mul_f32_e32 v38, v38, v41
	v_mul_f32_e32 v39, v39, v41
.Lcv_nogk1:
	s_cmp_ge_i32 s50, 64
	s_cbranch_scc1 .Lcv_full1
	v_cmp_gt_i32_e32 vcc, s50, v3
	s_nop 1
	v_cndmask_b32_e32 v32, 0, v32, vcc
	v_cndmask_b32_e32 v33, 0, v33, vcc
	v_cndmask_b32_e32 v34, 0, v34, vcc
	v_cndmask_b32_e32 v35, 0, v35, vcc
	v_cndmask_b32_e32 v36, 0, v36, vcc
	v_cndmask_b32_e32 v37, 0, v37, vcc
	v_cndmask_b32_e32 v38, 0, v38, vcc
	v_cndmask_b32_e32 v39, 0, v39, vcc
.Lcv_full1:
	ds_write2_b32 v8, v32, v33 offset1:1
	ds_write2_b32 v8, v34, v35 offset0:2 offset1:3
	ds_write2_b32 v9, v36, v37 offset1:1
	ds_write2_b32 v9, v38, v39 offset0:2 offset1:3
	s_waitcnt lgkmcnt(0)
	s_barrier
	s_and_b32 s2, s51, 3
	s_cmp_eq_u32 s2, 3
	s_cbranch_scc1 .Lcv_m31
	ds_read2_b32 v[72:73], v12 offset1:65
	ds_read2_b32 v[74:75], v12 offset0:130 offset1:195
	ds_read2_b32 v[76:77], v13 offset0:4 offset1:69
	ds_read2_b32 v[78:79], v13 offset0:134 offset1:199
	s_bitcmp1_b32 s51, 3
	s_movk_i32 s2, 0x800
	s_cbranch_scc0 .Lcv_k1
	s_movk_i32 s2, 0x1600
.Lcv_k1:
	v_mad_u32_u24 v71, v16, s2, v17
	s_waitcnt lgkmcnt(0)
	v_cvt_pk_bf16_f32 v72, v72, v73
	v_cvt_pk_bf16_f32 v73, v74, v75
	v_cvt_pk_bf16_f32 v74, v76, v77
	v_cvt_pk_bf16_f32 v75, v78, v79
	global_store_dwordx4 v71, v[72:75], s[44:45]
	s_branch .Lcv_st1
.Lcv_m31:
	ds_read2_b32 v[72:73], v15 offset1:1
	ds_read2_b32 v[74:75], v15 offset0:2 offset1:3
	ds_read2_b32 v[76:77], v15 offset0:4 offset1:5
	ds_read2_b32 v[78:79], v15 offset0:6 offset1:7
	s_waitcnt lgkmcnt(0)
	v_cvt_pk_bf16_f32 v72, v72, v73
	v_cvt_pk_bf16_f32 v73, v74, v75
	v_cvt_pk_bf16_f32 v74, v76, v77
	v_cvt_pk_bf16_f32 v75, v78, v79
	global_store_dwordx4 v18, v[72:75], s[44:45]
.Lcv_st1:
	s_add_u32 s36, s36, 1
	s_cmp_ge_u32 s36, s37
	s_cbranch_scc1 .Lcv_done
	s_add_u32 s38, s36, 3
	s_sub_u32 s2, s37, 1
	s_min_u32 s38, s38, s2
	s_mul_i32 s38, s38, 248
	s_add_u32 s38, s38, s39
	s_mov_b32 s79, 5
	s_branch .Lcv_desc
.Lcv_ret5:
	v_cmp_gt_i32_e32 vcc, s63, v3
	v_add_u32_e32 v70, s64, v2
	s_nop 1
	v_cndmask_b32_e32 v70, 0, v70, vcc
	v_mad_u32_u24 v70, v1, s62, v70
	global_load_dwordx4 v[32:35], v70, s[60:61]
	s_lshl_b32 s2, s62, 5
	s_add_u32 s60, s60, s2
	s_addc_u32 s61, s61, 0
	global_load_dwordx4 v[36:39], v70, s[60:61]
	global_load_dword v40, v4, s[66:67]
	global_load_dword v41, v4, s[66:67] offset:128
	s_mov_b64 s[44:45], s[70:71]
	s_mov_b32 s50, s63
	s_mov_b32 s51, s68
	s_waitcnt vmcnt(12)
	s_bitcmp1_b32 s55, 2
	s_cbranch_scc0 .Lcv_nogk2
	v_mul_f32_e32 v44, v44, v52
	v_mul_f32_e32 v45, v45, v52
	v_mul_f32_e32 v46, v46, v52
	v_mul_f32_e32 v47, v47, v52
	v_mul_f32_e32 v48, v48, v53
	v_mul_f32_e32 v49, v49, v53
	v_mul_f32_e32 v50, v50, v53
	v_mul_f32_e32 v51, v51, v53
; DEVI unsigned cvt_pk(float lo, float hi) { f32v2_t f = {lo, hi}; bf16v2_t v = __builtin_convertvector(f, bf16v2_t); return __builtin_bit_cast(unsigned, v); }
; DEVI void convT(const float* src, int K, int N, u16* dst, int Npad, int mode, const float* gk, float* tile, int first) {
;     ...
;         for (int i = tid; i < 1024; i += 512) { const int kk = i >> 4, n4 = (i & 15) * 4, n = n0 + n4;
;             f32x4 v = (f32x4){0.f, 0.f, 0.f, 0.f}; if (n < N) { v = *(const f32x4*)(src + (size_t)(k0 + kk) * N + n); if (gk) v = v * gk[k0 + kk]; }
;             float* tp = tile + kk * 65 + n4; tp[0] = v[0]; tp[1] = v[1]; tp[2] = v[2]; tp[3] = v[3]; }
;         __syncthreads();
;         if (mode == 3) { const int kk = tid >> 3, n8 = (tid & 7) * 8; const float* tp = tile + kk * 65 + n8;
;           u32x4 w; w.x = cvt_pk(tp[0], tp[1]); w.y = cvt_pk(tp[2], tp[3]); w.z = cvt_pk(tp[4], tp[5]); w.w = cvt_pk(tp[6], tp[7]);
;           *(u32x4*)(dst + (size_t)(k0 + kk) * N + n0 + n8) = w; }
;         else { const int nn = tid >> 3, k8 = (tid & 7) * 8; const int n = n0 + nn;
;           int row = n; if (mode == 1) row = 256 * (n >> 7) + (n & 127); else if (mode == 2) row = 256 * (n >> 7) + 128 + (n & 127);
;           u32x4 w; w.x = cvt_pk(tile[(k8 + 0) * 65 + nn], tile[(k8 + 1) * 65 + nn]); w.y = cvt_pk(tile[(k8 + 2) * 65 + nn], tile[(k8 + 3) * 65 + nn]);
;           w.z = cvt_pk(tile[(k8 + 4) * 65 + nn], tile[(k8 + 5) * 65 + nn]); w.w = cvt_pk(tile[(k8 + 6) * 65 + nn], tile[(k8 + 7) * 65 + nn]);
;           *(u32x4*)(dst + (size_t)row * K + k0 + k8) = w; }
;         __syncthreads();
; DEVI void conv_job(const Params& p, int job, const float*& src, int& K, int& N, u16*& dst, int& Npad, int& mode, const float*& gk) {
;     unsigned char* ws = p.ws; K = 1024; N = 1024; Npad = 1024; mode = 0; gk = nullptr;
;     if (job < 2) { src = p.in[7] + (size_t)job * 1024 * 3080; N = 3080; Npad = 3328; dst = (u16*)(ws + OFF_W_AIN + job * SZ_AIN); gk = p.in[2] + 3 * job * DM; }
.Lcv_nogk2:
	s_cmp_ge_i32 s54, 64
	s_cbranch_scc1 .Lcv_full2
	v_cmp_gt_i32_e32 vcc, s54, v3
	s_nop 1
	v_cndmask_b32_e32 v44, 0, v44, vcc
	v_cndmask_b32_e32 v45, 0, v45, vcc
	v_cndmask_b32_e32 v46, 0, v46, vcc
	v_cndmask_b32_e32 v47, 0, v47, vcc
	v_cndmask_b32_e32 v48, 0, v48, vcc
	v_cndmask_b32_e32 v49, 0, v49, vcc
	v_cndmask_b32_e32 v50, 0, v50, vcc
	v_cndmask_b32_e32 v51, 0, v51, vcc
.Lcv_full2:
	ds_write2_b32 v6, v44, v45 offset1:1
	ds_write2_b32 v6, v46, v47 offset0:2 offset1:3
	ds_write2_b32 v7, v48, v49 offset1:1
	ds_write2_b32 v7, v50, v51 offset0:2 offset1:3
	s_waitcnt lgkmcnt(0)
	s_barrier
	s_and_b32 s2, s55, 3
	s_cmp_eq_u32 s2, 3
	s_cbranch_scc1 .Lcv_m32
	ds_read2_b32 v[72:73], v10 offset1:65
	ds_read2_b32 v[74:75], v10 offset0:130 offset1:195
	ds_read2_b32 v[76:77], v11 offset0:4 offset1:69
	ds_read2_b32 v[78:79], v11 offset0:134 offset1:199
	s_bitcmp1_b32 s55, 3
	s_movk_i32 s2, 0x800
	s_cbranch_scc0 .Lcv_k2
	s_movk_i32 s2, 0x1600
.Lcv_k2:
	v_mad_u32_u24 v71, v16, s2, v17
	s_waitcnt lgkmcnt(0)
	v_cvt_pk_bf16_f32 v72, v72, v73
	v_cvt_pk_bf16_f32 v73, v74, v75
	v_cvt_pk_bf16_f32 v74, v76, v77
	v_cvt_pk_bf16_f32 v75, v78, v79
	global_store_dwordx4 v71, v[72:75], s[52:53]
	s_branch .Lcv_st2
.Lcv_m32:
	ds_read2_b32 v[72:73], v14 offset1:1
	ds_read2_b32 v[74:75], v14 offset0:2 offset1:3
	ds_read2_b32 v[76:77], v14 offset0:4 offset1:5
	ds_read2_b32 v[78:79], v14 offset0:6 offset1:7
	s_waitcnt lgkmcnt(0)
	v_cvt_pk_bf16_f32 v72, v72, v73
	v_cvt_pk_bf16_f32 v73, v74, v75
	v_cvt_pk_bf16_f32 v74, v76, v77
	v_cvt_pk_bf16_f32 v75, v78, v79
	global_store_dwordx4 v18, v[72:75], s[52:53]
.Lcv_st2:
	s_add_u32 s36, s36, 1
	s_cmp_ge_u32 s36, s37
	s_cbranch_scc1 .Lcv_done
	s_add_u32 s38, s36, 3
	s_sub_u32 s2, s37, 1
	s_min_u32 s38, s38, s2
	s_mul_i32 s38, s38, 248
	s_add_u32 s38, s38, s39
	s_mov_b32 s79, 6
	s_branch .Lcv_desc
.Lcv_ret6:
	v_cmp_gt_i32_e32 vcc, s63, v3
	v_add_u32_e32 v70, s64, v2
	s_nop 1
	v_cndmask_b32_e32 v70, 0, v70, vcc
	v_mad_u32_u24 v70, v1, s62, v70
	global_load_dwordx4 v[44:47], v70, s[60:61]
	s_lshl_b32 s2, s62, 5
	s_add_u32 s60, s60, s2
	s_addc_u32 s61, s61, 0
	global_load_dwordx4 v[48:51], v70, s[60:61]
	global_load_dword v52, v4, s[66:67]
	global_load_dword v53, v4, s[66:67] offset:128
	s_mov_b64 s[52:53], s[70:71]
	s_mov_b32 s54, s63
	s_mov_b32 s55, s68
	s_waitcnt vmcnt(12)
	s_bitcmp1_b32 s59, 2
	s_cbranch_scc0 .Lcv_nogk3
	v_mul_f32_e32 v56, v56, v64
	v_mul_f32_e32 v57, v57, v64
	v_mul_f32_e32 v58, v58, v64
	v_mul_f32_e32 v59, v59, v64
	v_mul_f32_e32 v60, v60, v65
	v_mul_f32_e32 v61, v61, v65
	v_mul_f32_e32 v62, v62, v65
	v_mul_f32_e32 v63, v63, v65
.Lcv_nogk3:
	s_cmp_ge_i32 s58, 64
	s_cbranch_scc1 .Lcv_full3
	v_cmp_gt_i32_e32 vcc, s58, v3
	s_nop 1
	v_cndmask_b32_e32 v56, 0, v56, vcc
	v_cndmask_b32_e32 v57, 0, v57, vcc
	v_cndmask_b32_e32 v58, 0, v58, vcc
	v_cndmask_b32_e32 v59, 0, v59, vcc
	v_cndmask_b32_e32 v60, 0, v60, vcc
	v_cndmask_b32_e32 v61, 0, v61, vcc
	v_cndmask_b32_e32 v62, 0, v62, vcc
	v_cndmask_b32_e32 v63, 0, v63, vcc
.Lcv_full3:
	ds_write2_b32 v8, v56, v57 offset1:1
	ds_write2_b32 v8, v58, v59 offset0:2 offset1:3
	ds_write2_b32 v9, v60, v61 offset1:1
	ds_write2_b32 v9, v62, v63 offset0:2 offset1:3
	s_waitcnt lgkmcnt(0)
	s_barrier
	s_and_b32 s2, s59, 3
	s_cmp_eq_u32 s2, 3
	s_cbranch_scc1 .Lcv_m33
	ds_read2_b32 v[72:73], v12 offset1:65
	ds_read2_b32 v[74:75], v12 offset0:130 offset1:195
	ds_read2_b32 v[76:77], v13 offset0:4 offset1:69
	ds_read2_b32 v[78:79], v13 offset0:134 offset1:199
	s_bitcmp1_b32 s59, 3
	s_movk_i32 s2, 0x800
	s_cbranch_scc0 .Lcv_k3
	s_movk_i32 s2, 0x1600
.Lcv_k3:
	v_mad_u32_u24 v71, v16, s2, v17
	s_waitcnt lgkmcnt(0)
	v_cvt_pk_bf16_f32 v72, v72, v73
	v_cvt_pk_bf16_f32 v73, v74, v75
	v_cvt_pk_bf16_f32 v74, v76, v77
	v_cvt_pk_bf16_f32 v75, v78, v79
	global_store_dwordx4 v71, v[72:75], s[56:57]
	s_branch .Lcv_st3
.Lcv_m33:
	ds_read2_b32 v[72:73], v15 offset1:1
	ds_read2_b32 v[74:75], v15 offset0:2 offset1:3
	ds_read2_b32 v[76:77], v15 offset0:4 offset1:5
	ds_read2_b32 v[78:79], v15 offset0:6 offset1:7
	s_waitcnt lgkmcnt(0)
	v_cvt_pk_bf16_f32 v72, v72, v73
	v_cvt_pk_bf16_f32 v73, v74, v75
	v_cvt_pk_bf16_f32 v74, v76, v77
	v_cvt_pk_bf16_f32 v75, v78, v79
	global_store_dwordx4 v18, v[72:75], s[56:57]
.Lcv_st3:
	s_add_u32 s36, s36, 1
	s_cmp_ge_u32 s36, s37
	s_cbranch_scc1 .Lcv_done
	s_branch .Lcv_loop
.Lcv_desc:
	s_mov_b32 s74, 1024
	s_mov_b32 s75, 16
	s_mov_b32 s76, 0
	s_mov_b32 s77, 0
	s_mov_b32 s78, 0
	s_mov_b32 s73, 0
	s_cmp_lt_u32 s38, 1664
	s_cbranch_scc0 .Lcvd1
	s_cmp_ge_u32 s38, 832
	s_cselect_b32 s5, 1, 0
	s_mul_i32 s4, s5, 832
	s_sub_u32 s4, s38, s4
	s_mov_b32 s72, 7
	s_mul_i32 s73, s5, 12615680
	s_mul_i32 s2, s5, 6815744
	s_mov_b32 s74, 3080
	s_mov_b32 s77, 2
	s_mul_i32 s78, s5, 12288
	s_branch .Lcvdt
; DEVI void convT(const float* src, int K, int N, u16* dst, int Npad, int mode, const float* gk, float* tile, int first) {
;     const int tid = otid(), ntk = K / 64, ntn = Npad / 64;
;     for (int ti = first; ti < ntk * ntn; ti += gridDim.x) {
;         const int k0 = (ti % ntk) * 64, n0 = (ti / ntk) * 64;
;         for (int i = tid; i < 1024; i += 512) { const int kk = i >> 4, n4 = (i & 15) * 4, n = n0 + n4;
; DEVI void conv_job(const Params& p, int job, const float*& src, int& K, int& N, u16*& dst, int& Npad, int& mode, const float*& gk) {
;     unsigned char* ws = p.ws; K = 1024; N = 1024; Npad = 1024; mode = 0; gk = nullptr;
;     if (job < 2) { src = p.in[7] + (size_t)job * 1024 * 3080; N = 3080; Npad = 3328; dst = (u16*)(ws + OFF_W_AIN + job * SZ_AIN); gk = p.in[2] + 3 * job * DM; }
;     else if (job < 4) { src = p.in[11] + (size_t)(job - 2) * 1024 * 1024; dst = (u16*)(ws + OFF_W_AOUT + (job - 2) * SZ_SQ); }
;     else if (job == 4) { src = p.in[12]; N = 3088; Npad = 3328; dst = (u16*)(ws + OFF_W_BIN); gk = p.in[2] + 1 * DM; }
;     else if (job == 5) { src = p.in[16]; dst = (u16*)(ws + OFF_W_BOUT); }
;     else if (job == 6) { src = p.in[17]; dst = (u16*)(ws + OFF_W_CIN); gk = p.in[2] + 2 * DM; }
;     else if (job == 7) { src = p.in[26]; dst = (u16*)(ws + OFF_W_CGATE); }
;     else if (job == 8) { src = p.in[28]; dst = (u16*)(ws + OFF_W_COUT); }
;     else if (job < 13) { const int i = job - 9; src = p.in[29] + (size_t)i * 1024 * 1024; dst = (u16*)(ws + OFF_W_XQ + i * SZ_SQ); gk = p.in[3] + i * DM; mode = 3; }
;     else if (job < 17) { const int i = job - 13; src = p.in[30] + (size_t)i * 1024 * 2048; N = 2048; Npad = 2048; dst = (u16*)(ws + OFF_W_XKV + i * 2 * SZ_SQ); }
;     else if (job < 21) { const int i = job - 17; src = p.in[31] + (size_t)i * 1024 * 1024; dst = (u16*)(ws + OFF_W_XO + i * SZ_SQ); }
;     else if (job < 25) { const int i = job - 21; src = p.in[32] + (size_t)i * 1024 * 2816; N = 2816; Npad = 2816; mode = 1; dst = (u16*)(ws + OFF_W_FGU + i * SZ_FGU); gk = p.in[4] + i * DM; }
;     else if (job < 29) { const int i = job - 25; src = p.in[33] + (size_t)i * 1024 * 2816; N = 2816; Npad = 2816; mode = 2; dst = (u16*)(ws + OFF_W_FGU + i * SZ_FGU); gk = p.in[4] + i * DM; }
;     else { const int i = job - 29; src = p.in[34] + (size_t)i * 2816 * 1024; K = 2816; dst = (u16*)(ws + OFF_W_FD + i * SZ_FD); }
; }
.Lcvd1:
	s_cmp_lt_u32 s38, 2176
	s_cbranch_scc0 .Lcvd2
	s_sub_u32 s4, s38, 1664
	s_lshr_b32 s5, s4, 8
	s_and_b32 s4, s4, 255
	s_mov_b32 s72, 11
	s_lshl_b32 s73, s5, 22
	s_lshl_b32 s2, s5, 21
	s_add_u32 s2, s2, 13631488
	s_branch .Lcvdt
.Lcvd2:
	s_cmp_lt_u32 s38, 3008
	s_cbranch_scc0 .Lcvd3
	s_sub_u32 s4, s38, 2176
	s_mov_b32 s72, 12
	s_mov_b32 s2, 17825792
	s_mov_b32 s74, 3088
	s_mov_b32 s77, 2
	s_mov_b32 s78, 4096
	s_branch .Lcvdt
.Lcvd3:
	s_cmp_lt_u32 s38, 4032
	s_cbranch_scc0 .Lcvd4
	s_sub_u32 s4, s38, 3008
	s_lshr_b32 s5, s4, 8
	s_and_b32 s4, s4, 255
	s_lshl_b32 s2, s5, 21
	s_add_u32 s2, s2, 24641536
	s_add_u32 s72, s5, 16
	s_lshl_b32 s10, s5, 1
	s_add_u32 s10, s10, 22
	s_cmp_lt_u32 s5, 2
	s_cselect_b32 s72, s72, s10
	s_cmp_eq_u32 s5, 1
	s_cselect_b32 s77, 2, 0
	s_cselect_b32 s78, 8192, 0
	s_branch .Lcvdt
.Lcvd4:
	s_cmp_lt_u32 s38, 5056
	s_cbranch_scc0 .Lcvd5
	s_sub_u32 s4, s38, 4032
	s_lshr_b32 s5, s4, 8
	s_and_b32 s4, s4, 255
	s_mov_b32 s72, 29
	s_lshl_b32 s73, s5, 22
	s_lshl_b32 s2, s5, 21
	s_add_u32 s2, s2, 33030144
	s_mov_b32 s77, 3
	s_lshl_b32 s78, s5, 12
	s_mov_b32 s76, 3
	s_branch .Lcvdt
.Lcvd5:
	s_cmp_lt_u32 s38, 7104
	s_cbranch_scc0 .Lcvd6
	s_sub_u32 s4, s38, 5056
	s_lshr_b32 s5, s4, 9
	s_and_b32 s4, s4, 511
	s_mov_b32 s72, 30
	s_lshl_b32 s73, s5, 23
	s_lshl_b32 s2, s5, 22
	s_add_u32 s2, s2, 41418752
	s_mov_b32 s74, 2048
	s_branch .Lcvdt
.Lcvd6:
	s_cmp_lt_u32 s38, 8128
	s_cbranch_scc0 .Lcvd7
	s_sub_u32 s4, s38, 7104
	s_lshr_b32 s5, s4, 8
	s_and_b32 s4, s4, 255
	s_mov_b32 s72, 31
	s_lshl_b32 s73, s5, 22
	s_lshl_b32 s2, s5, 21
	s_add_u32 s2, s2, 58195968
	s_branch .Lcvdt
.Lcvd7:
	s_cmp_lt_u32 s38, 13760
	s_cbranch_scc0 .Lcvd9
	s_cmp_lt_u32 s38, 10944
	s_cselect_b32 s72, 32, 33
	s_cselect_b32 s76, 1, 2
	s_movk_i32 s10, 0x1fc0
	s_cbranch_scc1 .Lcvd7a
	s_movk_i32 s10, 0x2ac0
.Lcvd7a:
	s_sub_u32 s4, s38, s10
	s_cmp_ge_u32 s4, 704
	s_cselect_b32 s5, 1, 0
	s_cmp_ge_u32 s4, 1408
	s_addc_u32 s5, s5, 0
	s_cmp_ge_u32 s4, 2112
	s_addc_u32 s5, s5, 0
	s_mul_i32 s10, s5, 704
	s_sub_u32 s4, s4, s10
	s_mul_i32 s73, s5, 11534336
	s_add_u32 s2, s73, 66584576
	s_mov_b32 s74, 2816
	s_mov_b32 s77, 4
	s_lshl_b32 s78, s5, 12
	s_branch .Lcvdt
.Lcvd9:
	s_sub_u32 s4, s38, 13760
	s_cmp_ge_u32 s4, 704
	s_cselect_b32 s5, 1, 0
	s_cmp_ge_u32 s4, 1408
	s_addc_u32 s5, s5, 0
	s_cmp_ge_u32 s4, 2112
	s_addc_u32 s5, s5, 0
	s_mul_i32 s10, s5, 704
	s_sub_u32 s4, s4, s10
	s_mov_b32 s72, 34
	s_mul_i32 s73, s5, 11534336
	s_mul_i32 s2, s5, 5767168
	s_add_u32 s2, s2, 112721920
	s_mov_b32 s75, 44
	s_mov_b32 s76, 8
.Lcvdt:
	s_cmp_eq_u32 s75, 16
	s_cbranch_scc0 .Lcvd44
	s_and_b32 s12, s4, 15
	s_lshr_b32 s13, s4, 4
	s_branch .Lcvdk
.Lcvd44:
	s_mul_i32 s13, s4, 1490
	s_lshr_b32 s13, s13, 16
	s_mul_i32 s12, s13, 44
	s_sub_u32 s12, s4, s12
.Lcvdk:
	s_lshl_b32 s12, s12, 6
	s_lshl_b32 s13, s13, 6
	s_lshl_b32 s5, s72, 3
	s_load_dwordx2 s[60:61], s[34:35], s5
	s_cmp_lg_u32 s77, 0
	s_cselect_b32 s10, s77, 2
	s_cselect_b32 s14, 4, 0
	s_or_b32 s76, s76, s14
	s_lshl_b32 s10, s10, 3
	s_load_dwordx2 s[66:67], s[34:35], s10
	s_mov_b32 s68, s76
	s_lshl_b32 s62, s74, 2
	s_sub_i32 s63, s74, s13
	s_lshl_b32 s64, s13, 2
	s_mul_i32 s5, s12, s74
	s_lshl_b32 s5, s5, 2
	s_add_u32 s5, s5, s73
	s_lshl_b32 s15, s12, 2
	s_add_u32 s15, s15, s78
	s_and_b32 s14, s76, 3
	s_cmp_eq_u32 s14, 3
	s_cbranch_scc0 .Lcvdm
	s_lshl_b32 s16, s12, 10
	s_add_u32 s16, s16, s13
	s_lshl_b32 s16, s16, 1
	s_branch .Lcvdo
.Lcvdm:
	s_mov_b32 s16, s13
	s_cmp_eq_u32 s14, 0
	s_cbranch_scc1 .Lcvdr
	s_lshr_b32 s16, s13, 7
	s_lshl_b32 s16, s16, 8
	s_and_b32 s17, s13, 64
	s_add_u32 s16, s16, s17
	s_cmp_eq_u32 s14, 2
	s_cselect_b32 s17, 128, 0
	s_add_u32 s16, s16, s17
.Lcvdr:
	s_movk_i32 s17, 0x400
	s_bitcmp1_b32 s76, 3
	s_cbranch_scc0 .Lcvdr2
	s_movk_i32 s17, 0xb00
.Lcvdr2:
	s_mul_i32 s16, s16, s17
	s_add_u32 s16, s16, s12
	s_lshl_b32 s16, s16, 1
.Lcvdo:
	s_add_u32 s2, s2, s16
	s_add_u32 s70, s20, s2
	s_addc_u32 s71, s21, 0
	s_waitcnt lgkmcnt(0)
	s_add_u32 s60, s60, s5
	s_addc_u32 s61, s61, 0
	s_add_u32 s66, s66, s15
	s_addc_u32 s67, s67, 0
	s_cmp_eq_u32 s79, 0
	s_cbranch_scc1 .Lcv_ret0
	s_cmp_eq_u32 s79, 1
	s_cbranch_scc1 .Lcv_ret1
	s_cmp_eq_u32 s79, 2
	s_cbranch_scc1 .Lcv_ret2
	s_cmp_eq_u32 s79, 3
	s_cbranch_scc1 .Lcv_ret3
	s_cmp_eq_u32 s79, 4
	s_cbranch_scc1 .Lcv_ret4
	s_cmp_eq_u32 s79, 5
	s_cbranch_scc1 .Lcv_ret5
	s_cmp_eq_u32 s79, 6
	s_cbranch_scc1 .Lcv_ret6
	s_branch .Lcv_ret0

; DEVI int otid() { int t = threadIdx.x; asm volatile("" : "+v"(t)); return t; }
; DEVI int obid() { int t = blockIdx.x; asm volatile("" : "+s"(t)); return t; }
; DEVI u32x2 pk4(f32x4 v) { u32x2 r; r.x = cvt_pk(v[0], v[1]); r.y = cvt_pk(v[2], v[3]); return r; }
; DEVI void rms_phase(const float* src, const float* g, u16* dst, int rows) {
;     const int lane = otid() & 63, gw = obid() * 8 + (otid() >> 6), nw = gridDim.x * 8;
;     f32x4 gv[4];
; #pragma unroll
;     for (int i = 0; i < 4; ++i) gv[i] = *(const f32x4*)(g + i * 256 + lane * 4);
;     for (int r = gw; r < rows; r += nw) {
;         const float* s = src + (size_t)r * DM; f32x4 v[4]; float ss = 0.f;
; #pragma unroll
;         for (int i = 0; i < 4; ++i) { v[i] = *(const f32x4*)(s + i * 256 + lane * 4); ss += v[i][0] * v[i][0] + v[i][1] * v[i][1] + v[i][2] * v[i][2] + v[i][3] * v[i][3]; }
; #pragma unroll
;         for (int o = 32; o > 0; o >>= 1) ss += __shfl_xor(ss, o);
;         const float rs = rsqrtf(ss * (1.f / DM) + 1e-6f);
; #pragma unroll
;         for (int i = 0; i < 4; ++i) *(u32x2*)(dst + (size_t)r * DM + i * 256 + lane * 4) = pk4(v[i] * rs * gv[i]);
;     }
.Lcv_end:
.LBB0_94:
	v_mov_b32_e32 v18, v154
	s_mov_b32 s0, s33
	v_mov_b32_e32 v0, v154
	s_lshl_b32 s4, s0, 3
	v_ashrrev_i32_e32 v16, 6, v0
	v_add_u32_e32 v20, s4, v16
	s_movk_i32 s0, 0x400
	s_lshl_b32 s2, s22, 3
	v_cmp_gt_i32_e32 vcc, s0, v20
	v_mbcnt_lo_u32_b32 v146, -1, 0
	s_and_saveexec_b64 s[0:1], vcc
	s_cbranch_execz .LBB0_97
	v_lshlrev_b32_e32 v0, 4, v18
	v_readlane_b32 s36, v251, 8
	v_and_b32_e32 v12, 0x3f0, v0
	v_readlane_b32 s46, v251, 18
	v_readlane_b32 s47, v251, 19
	s_nop 4
	global_load_dwordx4 v[0:3], v12, s[46:47]
	global_load_dwordx4 v[4:7], v12, s[46:47] offset:1024
	global_load_dwordx4 v[8:11], v12, s[46:47] offset:2048
	s_nop 0
	global_load_dwordx4 v[12:15], v12, s[46:47] offset:3072
	v_mbcnt_hi_u32_b32 v17, -1, v146
	v_and_b32_e32 v19, 64, v17
	v_add_u32_e32 v19, 64, v19
	v_xor_b32_e32 v21, 32, v17
	v_cmp_lt_i32_e32 vcc, v21, v19
	v_xor_b32_e32 v22, 16, v17
	v_xor_b32_e32 v23, 8, v17
	v_cndmask_b32_e32 v21, v17, v21, vcc
	v_cmp_lt_i32_e32 vcc, v22, v19
	v_xor_b32_e32 v24, 4, v17
	v_xor_b32_e32 v25, 2, v17
	v_cndmask_b32_e32 v22, v17, v22, vcc
	v_cmp_lt_i32_e32 vcc, v23, v19
	v_xor_b32_e32 v26, 1, v17
	s_ashr_i32 s5, s4, 31
	v_cndmask_b32_e32 v23, v17, v23, vcc
	v_cmp_lt_i32_e32 vcc, v24, v19
	v_readlane_b32 s37, v251, 9
	v_readlane_b32 s38, v251, 10
	v_cndmask_b32_e32 v24, v17, v24, vcc
	v_cmp_lt_i32_e32 vcc, v25, v19
	v_readlane_b32 s39, v251, 11
	s_mov_b64 s[16:17], s[36:37]
	v_cndmask_b32_e32 v25, v17, v25, vcc
	v_cmp_lt_i32_e32 vcc, v26, v19
	v_and_b32_e32 v27, 63, v18
	s_mov_b64 s[18:19], s[38:39]
	v_cndmask_b32_e32 v17, v17, v26, vcc
	v_lshlrev_b32_e32 v26, 2, v17
	v_ashrrev_i32_e32 v17, 31, v16
	v_lshl_add_u64 v[28:29], v[16:17], 0, s[4:5]
	v_lshlrev_b64 v[16:17], 11, v[28:29]
	v_lshlrev_b64 v[18:19], 12, v[28:29]
	v_lshl_or_b32 v16, v27, 3, v16
	v_lshl_or_b32 v18, v27, 4, v18
	v_lshl_add_u64 v[16:17], s[20:21], 0, v[16:17]
	s_mov_b64 s[4:5], 0x8180400
	s_ashr_i32 s3, s2, 31
	v_lshl_add_u64 v[18:19], s[18:19], 0, v[18:19]
	s_mov_b64 s[8:9], 0xc00
	v_lshlrev_b32_e32 v21, 2, v21
	v_lshlrev_b32_e32 v22, 2, v22
	v_lshlrev_b32_e32 v23, 2, v23
	v_lshlrev_b32_e32 v24, 2, v24
	v_lshlrev_b32_e32 v25, 2, v25
	v_lshl_add_u64 v[16:17], v[16:17], 0, s[4:5]
	s_lshl_b64 s[4:5], s[2:3], 11
	v_lshl_add_u64 v[18:19], v[18:19], 0, s[8:9]
	s_lshl_b64 s[8:9], s[2:3], 12
	s_mov_b64 s[10:11], 0
	v_mov_b32_e32 v27, 0x358637bd
	s_mov_b32 s12, 0x800000
	s_movk_i32 s13, 0x3ff
	v_readlane_b32 s40, v251, 12
	v_readlane_b32 s41, v251, 13
	v_readlane_b32 s42, v251, 14
	v_readlane_b32 s43, v251, 15
	v_readlane_b32 s44, v251, 16
	v_readlane_b32 s45, v251, 17
	v_readlane_b32 s48, v251, 20
	v_readlane_b32 s49, v251, 21
	v_readlane_b32 s50, v251, 22
	v_readlane_b32 s51, v251, 23

; __global__ void __launch_bounds__(512, 2) fwd_megakernel(Params p) {
	.amdhsa_kernel _Z14fwd_megakernel6Params
		.amdhsa_group_segment_fixed_size 0
		.amdhsa_private_segment_fixed_size 0
		.amdhsa_kernarg_size 552
		.amdhsa_user_sgpr_count 2
		.amdhsa_user_sgpr_dispatch_ptr 0
		.amdhsa_user_sgpr_queue_ptr 0
		.amdhsa_user_sgpr_kernarg_segment_ptr 1
		.amdhsa_user_sgpr_dispatch_id 0
		.amdhsa_user_sgpr_kernarg_preload_length 0
		.amdhsa_user_sgpr_kernarg_preload_offset 0
		.amdhsa_user_sgpr_private_segment_size 0
		.amdhsa_uses_dynamic_stack 0
		.amdhsa_enable_private_segment 0
		.amdhsa_system_sgpr_workgroup_id_x 1
		.amdhsa_system_sgpr_workgroup_id_y 0
		.amdhsa_system_sgpr_workgroup_id_z 0
		.amdhsa_system_sgpr_workgroup_info 0
		.amdhsa_system_vgpr_workitem_id 2
		.amdhsa_next_free_vgpr 256
		.amdhsa_next_free_sgpr 102
		.amdhsa_accum_offset 256
		.amdhsa_reserve_vcc 1
		.amdhsa_float_round_mode_32 0
		.amdhsa_float_round_mode_16_64 0
		.amdhsa_float_denorm_mode_32 3
		.amdhsa_float_denorm_mode_16_64 3
		.amdhsa_dx10_clamp 1
		.amdhsa_ieee_mode 1
		.amdhsa_fp16_overflow 0
		.amdhsa_tg_split 0
		.amdhsa_exception_fp_ieee_invalid_op 0
		.amdhsa_exception_fp_denorm_src 0
		.amdhsa_exception_fp_ieee_div_zero 0
		.amdhsa_exception_fp_ieee_overflow 0
		.amdhsa_exception_fp_ieee_underflow 0
		.amdhsa_exception_fp_ieee_inexact 0
		.amdhsa_exception_int_div_zero 0
	.end_amdhsa_kernel

; __global__ void __launch_bounds__(512, 2) fwd_megakernel(Params p) {
amdhsa.kernels:
  - .agpr_count:     0
    .args:
      - .offset:         0
        .size:           296
        .value_kind:     by_value
      - .offset:         296
        .size:           4
        .value_kind:     hidden_block_count_x
      - .offset:         300
        .size:           4
        .value_kind:     hidden_block_count_y
      - .offset:         304
        .size:           4
        .value_kind:     hidden_block_count_z
      - .offset:         308
        .size:           2
        .value_kind:     hidden_group_size_x
      - .offset:         310
        .size:           2
        .value_kind:     hidden_group_size_y
      - .offset:         312
        .size:           2
        .value_kind:     hidden_group_size_z
      - .offset:         314
        .size:           2
        .value_kind:     hidden_remainder_x
      - .offset:         316
        .size:           2
        .value_kind:     hidden_remainder_y
      - .offset:         318
        .size:           2
        .value_kind:     hidden_remainder_z
      - .offset:         336
        .size:           8
        .value_kind:     hidden_global_offset_x
      - .offset:         344
        .size:           8
        .value_kind:     hidden_global_offset_y
      - .offset:         352
        .size:           8
        .value_kind:     hidden_global_offset_z
      - .offset:         360
        .size:           2
        .value_kind:     hidden_grid_dims
      - .offset:         384
        .size:           8
        .value_kind:     hidden_multigrid_sync_arg
      - .offset:         416
        .size:           4
        .value_kind:     hidden_dynamic_lds_size
    .group_segment_fixed_size: 0
    .kernarg_segment_align: 8
    .kernarg_segment_size: 552
    .language:       OpenCL C
    .language_version:
      - 2
      - 0
    .max_flat_workgroup_size: 512
    .name:           _Z14fwd_megakernel6Params
    .private_segment_fixed_size: 0
    .sgpr_count:     108
    .sgpr_spill_count: 309
    .symbol:         _Z14fwd_megakernel6Params.kd
    .uniform_work_group_size: 1
    .uses_dynamic_stack: false
    .vgpr_count:     256
    .vgpr_spill_count: 0
    .wavefront_size: 64
